# attention 64 rows per wave: max-update, alpha and rescale moved entirely into the wave-uniform slow path (-Cc*m kept in a register), emitter now keeps pending LDS reads across conditionally skipped re
# baseline (speedup 1.0000x reference)
; #define SLOAD(i, k0) do { sr_[i].a0 = *reinterpret_cast<const bf16x8*>(&KVh[(size_t)((k0) + sr) * NKV + c16 * 8]); sr_[i].a1 = *reinterpret_cast<const bf16x8*>(&KVh[(size_t)((k0) + 32 + sr) * NKV + c16 * 8]); \
;     sr_[i].rr = *reinterpret_cast<const bf16x8*>(&KR[(size_t)((k0) + rkey) * 32 + rch * 8]); } while (0)
; #define SWRITE(b, i) do { if (isK) { *(bf16x8*)(K_lds + (b) * SHM_K + kst0) = sr_[i].a0; *(bf16x8*)(K_lds + (b) * SHM_K + kst1) = sr_[i].a1; } \
;     else { *(bf16x8*)(V_lds + (b) * SHM_V + vst0) = sr_[i].a0; *(bf16x8*)(V_lds + (b) * SHM_V + vst1) = sr_[i].a1; } \
;     if (rwr) *(bf16x8*)(K_lds + (b) * SHM_K + rst) = sr_[i].rr; } while (0)
; #define SWAIT() asm volatile("s_waitcnt vmcnt(3)" ::: "memory")
; __device__ __forceinline__ void attn_body(const bf16_t* __restrict__ Qb, const bf16_t* __restrict__ KVh, const bf16_t* __restrict__ KR, const float* __restrict__ ropeq,
;                                           bf16_t* __restrict__ Ob, int seq, char* lds, const int tid) {
;     ...
;     float m_reg = -1e30f, l_reg = 0; f32x16 o[2] = {}; bf16x8 qr[6];
;     ...
;     SLOAD(SO, KVBLK); if (2 < NT) SLOAD(SE, 2 * KVBLK);
;     SWAIT(); SWRITE(1, SO); __syncthreads();
.LA_swp:
	v_add_u32_e32 v247, 0x20000, v243
	global_load_dwordx4 v[228:231], v243, s[28:29]
	global_load_dwordx4 v[130:133], v247, s[28:29]
	global_load_dwordx4 v[248:251], v244, s[44:45]
	s_add_u32 s28, s28, 0x40000
	s_addc_u32 s29, s29, 0
	s_add_u32 s44, s44, 0x1000
	s_addc_u32 s45, s45, 0
	v_mov_b32_e32 v141, 0xf149f2ca
	v_mov_b32_e32 v254, 0
	v_mov_b32_e32 v64, 0
	v_mov_b32_e32 v0, 0
	v_mov_b32_e32 v1, 0
	v_mov_b32_e32 v2, 0
	v_mov_b32_e32 v3, 0
	v_mov_b32_e32 v4, 0
	v_mov_b32_e32 v5, 0
	v_mov_b32_e32 v6, 0
	v_mov_b32_e32 v7, 0
	v_mov_b32_e32 v8, 0
	v_mov_b32_e32 v9, 0
	v_mov_b32_e32 v10, 0
	v_mov_b32_e32 v11, 0
	v_mov_b32_e32 v12, 0
	v_mov_b32_e32 v13, 0
	v_mov_b32_e32 v14, 0
	v_mov_b32_e32 v15, 0
	v_mov_b32_e32 v16, 0
	v_mov_b32_e32 v17, 0
	v_mov_b32_e32 v18, 0
	v_mov_b32_e32 v19, 0
	v_mov_b32_e32 v20, 0
	v_mov_b32_e32 v21, 0
	v_mov_b32_e32 v22, 0
	v_mov_b32_e32 v23, 0
	v_mov_b32_e32 v24, 0
	v_mov_b32_e32 v25, 0
	v_mov_b32_e32 v26, 0
	v_mov_b32_e32 v27, 0
	v_mov_b32_e32 v28, 0
	v_mov_b32_e32 v29, 0
	v_mov_b32_e32 v30, 0
	v_mov_b32_e32 v31, 0
	v_mov_b32_e32 v139, 0xf149f2ca
	v_mov_b32_e32 v255, 0
	v_mov_b32_e32 v134, 0
	v_mov_b32_e32 v32, 0
	v_mov_b32_e32 v33, 0
	v_mov_b32_e32 v34, 0
	v_mov_b32_e32 v35, 0
	v_mov_b32_e32 v36, 0
	v_mov_b32_e32 v37, 0
	v_mov_b32_e32 v38, 0
	v_mov_b32_e32 v39, 0
	v_mov_b32_e32 v40, 0
	v_mov_b32_e32 v41, 0
	v_mov_b32_e32 v42, 0
	v_mov_b32_e32 v43, 0
	v_mov_b32_e32 v44, 0
	v_mov_b32_e32 v45, 0
	v_mov_b32_e32 v46, 0
	v_mov_b32_e32 v47, 0
	v_mov_b32_e32 v48, 0
	v_mov_b32_e32 v49, 0
	v_mov_b32_e32 v50, 0
	v_mov_b32_e32 v51, 0
	v_mov_b32_e32 v52, 0
	v_mov_b32_e32 v53, 0
	v_mov_b32_e32 v54, 0
	v_mov_b32_e32 v55, 0
	v_mov_b32_e32 v56, 0
	v_mov_b32_e32 v57, 0
	v_mov_b32_e32 v58, 0
	v_mov_b32_e32 v59, 0
	v_mov_b32_e32 v60, 0
	v_mov_b32_e32 v61, 0
	v_mov_b32_e32 v62, 0
	v_mov_b32_e32 v63, 0
	s_waitcnt lgkmcnt(0)
	s_barrier

; __device__ __forceinline__ void partialSM(f32x16& p0, f32x16& p1, float& m_reg, float& mn, float& alpha) {
;     constexpr float Cc = SCALE * 1.4426950408889634f;
;     float pmax = p0[0];
; #pragma unroll
;     for (int r = 1; r < 16; ++r) pmax = fmaxf(pmax, p0[r]);
; #pragma unroll
;     for (int r = 0; r < 16; ++r) pmax = fmaxf(pmax, p1[r]);
;     { auto rr = __builtin_amdgcn_permlane32_swap(__float_as_uint(pmax), __float_as_uint(pmax), false, false);
;       pmax = fmaxf(__uint_as_float(rr[0]), __uint_as_float(rr[1])); }
;     if (__builtin_expect(__all(pmax - m_reg <= THR / SCALE), 1)) { mn = m_reg; alpha = 1.f; }
;     else { mn = fmaxf(m_reg, pmax); alpha = __builtin_amdgcn_exp2f((m_reg - mn) * Cc); m_reg = mn; }
;     const float mnC = -mn * Cc;
;     { typedef float f32x2 __attribute__((ext_vector_type(2))); const f32x2 c2 = {Cc, Cc}, m2 = {mnC, mnC};
; #pragma unroll
;       for (int r = 0; r < 16; r += 2) { f32x2 t = {p0[r], p0[r + 1]}; t = __builtin_elementwise_fma(t, c2, m2); p0[r] = t.x; p0[r + 1] = t.y; }
; #pragma unroll
;       for (int r = 0; r < 16; r += 2) { f32x2 t = {p1[r], p1[r + 1]}; t = __builtin_elementwise_fma(t, c2, m2); p1[r] = t.x; p1[r + 1] = t.y; } }
; #pragma unroll
;     for (int r = 0; r < 16; ++r) p0[r] = __builtin_amdgcn_exp2f(p0[r]);
; }
.LA_nosw:
	v_add_u32_e32 v202, s18, v235
	v_max_f32_e32 v212, v66, v67
	v_max_f32_e32 v213, v82, v83
	v_max3_f32 v212, v212, v68, v69
	v_max3_f32 v213, v213, v84, v85
	v_max3_f32 v212, v212, v70, v71
	v_max3_f32 v213, v213, v86, v87
	v_max3_f32 v212, v212, v72, v73
	v_max3_f32 v213, v213, v88, v89
	v_max3_f32 v212, v212, v74, v75
	v_max3_f32 v213, v213, v90, v91
	v_max3_f32 v212, v212, v76, v77
	v_max3_f32 v213, v213, v92, v93
	v_max3_f32 v212, v212, v78, v79
	v_max3_f32 v213, v213, v94, v95
	v_max3_f32 v212, v212, v80, v81
	v_max3_f32 v213, v213, v96, v97
	v_max_f32_e32 v212, v212, v213
	v_mov_b32_e32 v213, v212
	s_nop 1
	v_permlane32_swap_b32_e32 v212, v213
	v_max_f32_e32 v212, v212, v213
	v_sub_f32_e32 v214, v212, v141
	v_cmp_ge_f32_e32 vcc, s67, v214
	s_nop 1
	s_cmp_eq_u64 vcc, exec
	s_cbranch_scc1 .LA_ok0
	v_max_f32_e32 v212, v141, v212
	v_sub_f32_e32 v214, v141, v212
	v_mul_f32_e32 v214, 0x3e16c740, v214
	v_exp_f32_e32 v215, v214
	v_mov_b32_e32 v141, v212
	v_mul_f32_e32 v64, 0xbe16c740, v212
	v_mul_f32_e32 v254, v254, v215
	s_and_saveexec_b64 s[60:61], s[4:5]
	ds_write_b32 v234, v215 offset:128
	s_or_b64 exec, exec, s[60:61]
	s_waitcnt lgkmcnt(0)
	v_add_u32_e32 v245, v232, v233
	ds_read_b128 v[220:223], v245 offset:224
	ds_read_b128 v[224:227], v245 offset:192
	ds_read_b128 v[216:219], v245 offset:160
	ds_read_b128 v[212:215], v245 offset:128
	s_waitcnt lgkmcnt(0)
	s_waitcnt lgkmcnt(3)
	v_mul_f32_e32 v12, v12, v220
	v_mul_f32_e32 v13, v13, v221
	v_mul_f32_e32 v14, v14, v222
	v_mul_f32_e32 v15, v15, v223
	s_waitcnt lgkmcnt(2)
	v_mul_f32_e32 v8, v8, v224
	v_mul_f32_e32 v9, v9, v225
	v_mul_f32_e32 v10, v10, v226
	v_mul_f32_e32 v11, v11, v227
	s_waitcnt lgkmcnt(1)
	v_mul_f32_e32 v4, v4, v216
	v_mul_f32_e32 v5, v5, v217
	v_mul_f32_e32 v6, v6, v218
	v_mul_f32_e32 v7, v7, v219
	s_waitcnt lgkmcnt(0)
	v_mul_f32_e32 v0, v0, v212
	v_mul_f32_e32 v1, v1, v213
	v_mul_f32_e32 v2, v2, v214
	v_mul_f32_e32 v3, v3, v215
	v_mul_f32_e32 v28, v28, v220
	v_mul_f32_e32 v29, v29, v221
	v_mul_f32_e32 v30, v30, v222
	v_mul_f32_e32 v31, v31, v223
	v_mul_f32_e32 v24, v24, v224
	v_mul_f32_e32 v25, v25, v225
	v_mul_f32_e32 v26, v26, v226
	v_mul_f32_e32 v27, v27, v227
	v_mul_f32_e32 v20, v20, v216
	v_mul_f32_e32 v21, v21, v217
	v_mul_f32_e32 v22, v22, v218
	v_mul_f32_e32 v23, v23, v219
	v_mul_f32_e32 v16, v16, v212
	v_mul_f32_e32 v17, v17, v213
	v_mul_f32_e32 v18, v18, v214
	v_mul_f32_e32 v19, v19, v215
.LA_ok0:
	v_fma_f32 v66, v66, s52, v64
	v_fma_f32 v67, v67, s52, v64
	v_fma_f32 v68, v68, s52, v64
	v_fma_f32 v69, v69, s52, v64
	v_fma_f32 v70, v70, s52, v64
	v_fma_f32 v71, v71, s52, v64
	v_fma_f32 v72, v72, s52, v64
	v_fma_f32 v73, v73, s52, v64
	v_fma_f32 v74, v74, s52, v64
	v_fma_f32 v75, v75, s52, v64
	v_fma_f32 v76, v76, s52, v64
	v_fma_f32 v77, v77, s52, v64
	v_fma_f32 v78, v78, s52, v64
	v_fma_f32 v79, v79, s52, v64
	v_fma_f32 v80, v80, s52, v64
	v_fma_f32 v81, v81, s52, v64
	v_fma_f32 v82, v82, s52, v64
	v_fma_f32 v83, v83, s52, v64
	v_fma_f32 v84, v84, s52, v64
	v_fma_f32 v85, v85, s52, v64
	v_fma_f32 v86, v86, s52, v64
	v_fma_f32 v87, v87, s52, v64
	v_fma_f32 v88, v88, s52, v64
	v_fma_f32 v89, v89, s52, v64
	v_fma_f32 v90, v90, s52, v64
	v_fma_f32 v91, v91, s52, v64
	v_fma_f32 v92, v92, s52, v64
	v_fma_f32 v93, v93, s52, v64
	v_fma_f32 v94, v94, s52, v64
	v_fma_f32 v95, v95, s52, v64
	v_fma_f32 v96, v96, s52, v64
	v_fma_f32 v97, v97, s52, v64
	v_exp_f32_e32 v66, v66
	v_exp_f32_e32 v67, v67
	v_exp_f32_e32 v68, v68
	v_exp_f32_e32 v69, v69
	v_exp_f32_e32 v70, v70
	v_exp_f32_e32 v71, v71
	v_exp_f32_e32 v72, v72
	v_exp_f32_e32 v73, v73
	v_exp_f32_e32 v74, v74
	v_exp_f32_e32 v75, v75
	v_exp_f32_e32 v76, v76
	v_exp_f32_e32 v77, v77
	v_exp_f32_e32 v78, v78
	v_exp_f32_e32 v79, v79
	v_exp_f32_e32 v80, v80
	v_exp_f32_e32 v81, v81
	v_exp_f32_e32 v82, v82
	v_exp_f32_e32 v83, v83
	v_exp_f32_e32 v84, v84
	v_exp_f32_e32 v85, v85
	v_exp_f32_e32 v86, v86
	v_exp_f32_e32 v87, v87
	v_exp_f32_e32 v88, v88
	v_exp_f32_e32 v89, v89
	v_exp_f32_e32 v90, v90
	v_exp_f32_e32 v91, v91
	v_exp_f32_e32 v92, v92
	v_exp_f32_e32 v93, v93
	v_exp_f32_e32 v94, v94
	v_exp_f32_e32 v95, v95
	v_exp_f32_e32 v96, v96
	v_exp_f32_e32 v97, v97
	v_add_f32_e32 v212, v66, v68
	v_add_f32_e32 v213, v67, v69
	v_add_f32_e32 v212, v70, v212
	v_add_f32_e32 v213, v71, v213
	v_add_f32_e32 v212, v72, v212
	v_add_f32_e32 v213, v73, v213
	v_add_f32_e32 v212, v74, v212
	v_add_f32_e32 v213, v75, v213
	v_add_f32_e32 v212, v76, v212
	v_add_f32_e32 v213, v77, v213
	v_add_f32_e32 v212, v78, v212
	v_add_f32_e32 v213, v79, v213
	v_add_f32_e32 v212, v80, v212
	v_add_f32_e32 v213, v81, v213
	v_add_f32_e32 v212, v82, v212
	v_add_f32_e32 v213, v83, v213
	v_add_f32_e32 v212, v84, v212
	v_add_f32_e32 v213, v85, v213
	v_add_f32_e32 v212, v86, v212
	v_add_f32_e32 v213, v87, v213
	v_add_f32_e32 v212, v88, v212
	v_add_f32_e32 v213, v89, v213
	v_add_f32_e32 v212, v90, v212
	v_add_f32_e32 v213, v91, v213
	v_add_f32_e32 v212, v92, v212
	v_add_f32_e32 v213, v93, v213
	v_add_f32_e32 v212, v94, v212
	v_add_f32_e32 v213, v95, v213
	v_add_f32_e32 v212, v96, v212
	v_add_f32_e32 v213, v97, v213
	v_add_f32_e32 v212, v212, v213
	v_add_f32_e32 v254, v254, v212
	v_cvt_pk_bf16_f32 v66, v66, v67
	v_cvt_pk_bf16_f32 v67, v68, v69
	v_cvt_pk_bf16_f32 v68, v70, v71
	v_cvt_pk_bf16_f32 v69, v72, v73
	v_cvt_pk_bf16_f32 v70, v74, v75
	v_cvt_pk_bf16_f32 v71, v76, v77
	v_cvt_pk_bf16_f32 v72, v78, v79
	v_cvt_pk_bf16_f32 v73, v80, v81
	v_cvt_pk_bf16_f32 v82, v82, v83
	v_cvt_pk_bf16_f32 v83, v84, v85
	v_cvt_pk_bf16_f32 v84, v86, v87
	v_cvt_pk_bf16_f32 v85, v88, v89
	v_cvt_pk_bf16_f32 v86, v90, v91
	v_cvt_pk_bf16_f32 v87, v92, v93
	v_cvt_pk_bf16_f32 v88, v94, v95
	v_cvt_pk_bf16_f32 v89, v96, v97
	v_permlane32_swap_b32_e32 v66, v68
	v_permlane32_swap_b32_e32 v67, v69
	v_permlane32_swap_b32_e32 v70, v72
	v_permlane32_swap_b32_e32 v71, v73
	v_permlane32_swap_b32_e32 v82, v84
	v_permlane32_swap_b32_e32 v83, v85
	v_permlane32_swap_b32_e32 v86, v88
	v_permlane32_swap_b32_e32 v87, v89
	s_waitcnt lgkmcnt(0)
	s_cmp_eq_u64 s[2:3], 0
	s_cbranch_scc0 .LA_g1b
	s_barrier
; __device__ __forceinline__ void partialSM(f32x16& p0, f32x16& p1, float& m_reg, float& mn, float& alpha) {
;     constexpr float Cc = SCALE * 1.4426950408889634f;
;     float pmax = p0[0];
; #pragma unroll
;     for (int r = 1; r < 16; ++r) pmax = fmaxf(pmax, p0[r]);
; #pragma unroll
;     for (int r = 0; r < 16; ++r) pmax = fmaxf(pmax, p1[r]);
;     { auto rr = __builtin_amdgcn_permlane32_swap(__float_as_uint(pmax), __float_as_uint(pmax), false, false);
;       pmax = fmaxf(__uint_as_float(rr[0]), __uint_as_float(rr[1])); }
;     if (__builtin_expect(__all(pmax - m_reg <= THR / SCALE), 1)) { mn = m_reg; alpha = 1.f; }
;     else { mn = fmaxf(m_reg, pmax); alpha = __builtin_amdgcn_exp2f((m_reg - mn) * Cc); m_reg = mn; }
.LA_g1b:
	ds_read_b64_tr_b16 v[74:75], v202 offset:0
	ds_read_b64_tr_b16 v[76:77], v202 offset:2048
	ds_read_b64_tr_b16 v[78:79], v202 offset:4096
	ds_read_b64_tr_b16 v[80:81], v202 offset:6144
	ds_read_b64_tr_b16 v[90:91], v202 offset:8192
	ds_read_b64_tr_b16 v[92:93], v202 offset:10240
	ds_read_b64_tr_b16 v[94:95], v202 offset:12288
	ds_read_b64_tr_b16 v[96:97], v202 offset:14336
	v_max_f32_e32 v212, v98, v99
	v_max_f32_e32 v213, v114, v115
	v_max3_f32 v212, v212, v100, v101
	v_max3_f32 v213, v213, v116, v117
	v_max3_f32 v212, v212, v102, v103
	v_max3_f32 v213, v213, v118, v119
	v_max3_f32 v212, v212, v104, v105
	v_max3_f32 v213, v213, v120, v121
	v_max3_f32 v212, v212, v106, v107
	v_max3_f32 v213, v213, v122, v123
	v_max3_f32 v212, v212, v108, v109
	v_max3_f32 v213, v213, v124, v125
	v_max3_f32 v212, v212, v110, v111
	v_max3_f32 v213, v213, v126, v127
	v_max3_f32 v212, v212, v112, v113
	v_max3_f32 v213, v213, v128, v129
	v_max_f32_e32 v212, v212, v213
	v_mov_b32_e32 v213, v212
	s_nop 1
	v_permlane32_swap_b32_e32 v212, v213
	v_max_f32_e32 v212, v212, v213
	v_sub_f32_e32 v214, v212, v139
	v_cmp_ge_f32_e32 vcc, s67, v214
	s_nop 1
	s_cmp_eq_u64 vcc, exec
	s_cbranch_scc1 .LA_ok1
	v_max_f32_e32 v212, v139, v212
	v_sub_f32_e32 v214, v139, v212
	v_mul_f32_e32 v214, 0x3e16c740, v214
	v_exp_f32_e32 v215, v214
	v_mov_b32_e32 v139, v212
	v_mul_f32_e32 v134, 0xbe16c740, v212
	v_mul_f32_e32 v255, v255, v215
	s_and_saveexec_b64 s[60:61], s[4:5]
	ds_write_b32 v234, v215 offset:128
	s_or_b64 exec, exec, s[60:61]
	s_waitcnt lgkmcnt(0)
	v_add_u32_e32 v245, v232, v233
	ds_read_b128 v[220:223], v245 offset:224
	ds_read_b128 v[224:227], v245 offset:192
	ds_read_b128 v[216:219], v245 offset:160
	ds_read_b128 v[212:215], v245 offset:128
	s_waitcnt lgkmcnt(0)
	s_waitcnt lgkmcnt(3)
	v_mul_f32_e32 v44, v44, v220
	v_mul_f32_e32 v45, v45, v221
	v_mul_f32_e32 v46, v46, v222
	v_mul_f32_e32 v47, v47, v223
	s_waitcnt lgkmcnt(2)
	v_mul_f32_e32 v40, v40, v224
	v_mul_f32_e32 v41, v41, v225
	v_mul_f32_e32 v42, v42, v226
	v_mul_f32_e32 v43, v43, v227
	s_waitcnt lgkmcnt(1)
	v_mul_f32_e32 v36, v36, v216
	v_mul_f32_e32 v37, v37, v217
	v_mul_f32_e32 v38, v38, v218
	v_mul_f32_e32 v39, v39, v219
	s_waitcnt lgkmcnt(0)
	v_mul_f32_e32 v32, v32, v212
	v_mul_f32_e32 v33, v33, v213
	v_mul_f32_e32 v34, v34, v214
	v_mul_f32_e32 v35, v35, v215
	v_mul_f32_e32 v60, v60, v220
	v_mul_f32_e32 v61, v61, v221
	v_mul_f32_e32 v62, v62, v222
	v_mul_f32_e32 v63, v63, v223
	v_mul_f32_e32 v56, v56, v224
	v_mul_f32_e32 v57, v57, v225
	v_mul_f32_e32 v58, v58, v226
	v_mul_f32_e32 v59, v59, v227
	v_mul_f32_e32 v52, v52, v216
	v_mul_f32_e32 v53, v53, v217
	v_mul_f32_e32 v54, v54, v218
	v_mul_f32_e32 v55, v55, v219
	v_mul_f32_e32 v48, v48, v212
	v_mul_f32_e32 v49, v49, v213
	v_mul_f32_e32 v50, v50, v214
	v_mul_f32_e32 v51, v51, v215
; __device__ __forceinline__ void partialSM(f32x16& p0, f32x16& p1, float& m_reg, float& mn, float& alpha) {
;     ...
;     const float mnC = -mn * Cc;
;     { typedef float f32x2 __attribute__((ext_vector_type(2))); const f32x2 c2 = {Cc, Cc}, m2 = {mnC, mnC};
; #pragma unroll
;       for (int r = 0; r < 16; r += 2) { f32x2 t = {p0[r], p0[r + 1]}; t = __builtin_elementwise_fma(t, c2, m2); p0[r] = t.x; p0[r + 1] = t.y; }
; #pragma unroll
;       for (int r = 0; r < 16; r += 2) { f32x2 t = {p1[r], p1[r + 1]}; t = __builtin_elementwise_fma(t, c2, m2); p1[r] = t.x; p1[r + 1] = t.y; } }
; #pragma unroll
;     for (int r = 0; r < 16; ++r) p0[r] = __builtin_amdgcn_exp2f(p0[r]);
; }
; __device__ __forceinline__ void finishSM(f32x16& p0, f32x16& p1, float alpha, float& l_reg, bf16x8& pa0, bf16x8& pa1, bf16x8& pa2, bf16x8& pa3) {
; #pragma unroll
;     for (int r = 0; r < 16; ++r) p1[r] = __builtin_amdgcn_exp2f(p1[r]);
;     float ps;
;     { typedef float f32x2 __attribute__((ext_vector_type(2))); f32x2 s0 = {p0[0], p0[1]}, s1 = {p1[0], p1[1]};
; #pragma unroll
;       for (int r = 2; r < 16; r += 2) { s0 += (f32x2){p0[r], p0[r + 1]}; s1 += (f32x2){p1[r], p1[r + 1]}; }
;       s0 += s1; ps = s0.x + s0.y; }
;     { auto rr = __builtin_amdgcn_permlane32_swap(__float_as_uint(ps), __float_as_uint(ps), false, false);
;       ps = __uint_as_float(rr[0]) + __uint_as_float(rr[1]); }
;     l_reg = l_reg * alpha + ps;
;     ...
;     PK4(p0, 0, pa0); PK4(p0, 8, pa1); PK4(p1, 0, pa2); PK4(p1, 8, pa3);
;     ...
; }
; template <int D0> __device__ __forceinline__ void pv_one(f32x16& od, int vb, bf16x8 pa0, bf16x8 pa1, bf16x8 pa2, bf16x8 pa3) {
;     const s16x4 l0 = tr_read<v_rd_off(D0, 0, 0)>(vb), h0 = tr_read<v_rd_off(D0, 0, 1)>(vb), l1 = tr_read<v_rd_off(D0, 1, 0)>(vb), h1 = tr_read<v_rd_off(D0, 1, 1)>(vb);
;     const s16x4 l2 = tr_read<v_rd_off(D0, 2, 0)>(vb), h2 = tr_read<v_rd_off(D0, 2, 1)>(vb), l3 = tr_read<v_rd_off(D0, 3, 0)>(vb), h3 = tr_read<v_rd_off(D0, 3, 1)>(vb);
;     asm volatile("s_waitcnt lgkmcnt(0)" ::: "memory"); SBAR();
;     ...
;     od = __builtin_amdgcn_mfma_f32_32x32x16_bf16(pa0, PK(l0, h0), od, 0, 0, 0);
;     od = __builtin_amdgcn_mfma_f32_32x32x16_bf16(pa1, PK(l1, h1), od, 0, 0, 0);
;     od = __builtin_amdgcn_mfma_f32_32x32x16_bf16(pa2, PK(l2, h2), od, 0, 0, 0);
;     od = __builtin_amdgcn_mfma_f32_32x32x16_bf16(pa3, PK(l3, h3), od, 0, 0, 0);
.LA_ok1:
	v_fma_f32 v98, v98, s52, v134
	v_fma_f32 v99, v99, s52, v134
	v_fma_f32 v100, v100, s52, v134
	v_fma_f32 v101, v101, s52, v134
	v_fma_f32 v102, v102, s52, v134
	v_fma_f32 v103, v103, s52, v134
	v_fma_f32 v104, v104, s52, v134
	v_fma_f32 v105, v105, s52, v134
	v_fma_f32 v106, v106, s52, v134
	v_fma_f32 v107, v107, s52, v134
	v_fma_f32 v108, v108, s52, v134
	v_fma_f32 v109, v109, s52, v134
	v_fma_f32 v110, v110, s52, v134
	v_fma_f32 v111, v111, s52, v134
	v_fma_f32 v112, v112, s52, v134
	v_fma_f32 v113, v113, s52, v134
	v_fma_f32 v114, v114, s52, v134
	v_fma_f32 v115, v115, s52, v134
	v_fma_f32 v116, v116, s52, v134
	v_fma_f32 v117, v117, s52, v134
	v_fma_f32 v118, v118, s52, v134
	v_fma_f32 v119, v119, s52, v134
	v_fma_f32 v120, v120, s52, v134
	v_fma_f32 v121, v121, s52, v134
	v_fma_f32 v122, v122, s52, v134
	v_fma_f32 v123, v123, s52, v134
	v_fma_f32 v124, v124, s52, v134
	v_fma_f32 v125, v125, s52, v134
	v_fma_f32 v126, v126, s52, v134
	v_fma_f32 v127, v127, s52, v134
	v_fma_f32 v128, v128, s52, v134
	v_fma_f32 v129, v129, s52, v134
	v_exp_f32_e32 v98, v98
	v_exp_f32_e32 v99, v99
	v_exp_f32_e32 v100, v100
	v_exp_f32_e32 v101, v101
	v_exp_f32_e32 v102, v102
	v_exp_f32_e32 v103, v103
	v_exp_f32_e32 v104, v104
	v_exp_f32_e32 v105, v105
	v_exp_f32_e32 v106, v106
	v_exp_f32_e32 v107, v107
	v_exp_f32_e32 v108, v108
	v_exp_f32_e32 v109, v109
	v_exp_f32_e32 v110, v110
	v_exp_f32_e32 v111, v111
	v_exp_f32_e32 v112, v112
	v_exp_f32_e32 v113, v113
	v_exp_f32_e32 v114, v114
	v_exp_f32_e32 v115, v115
	v_exp_f32_e32 v116, v116
	v_exp_f32_e32 v117, v117
	v_exp_f32_e32 v118, v118
	v_exp_f32_e32 v119, v119
	v_exp_f32_e32 v120, v120
	v_exp_f32_e32 v121, v121
	v_exp_f32_e32 v122, v122
	v_exp_f32_e32 v123, v123
	v_exp_f32_e32 v124, v124
	v_exp_f32_e32 v125, v125
	v_exp_f32_e32 v126, v126
	v_exp_f32_e32 v127, v127
	v_exp_f32_e32 v128, v128
	v_exp_f32_e32 v129, v129
	v_add_f32_e32 v212, v98, v100
	v_add_f32_e32 v213, v99, v101
	v_add_f32_e32 v212, v102, v212
	v_add_f32_e32 v213, v103, v213
	v_add_f32_e32 v212, v104, v212
	v_add_f32_e32 v213, v105, v213
	v_add_f32_e32 v212, v106, v212
	v_add_f32_e32 v213, v107, v213
	v_add_f32_e32 v212, v108, v212
	v_add_f32_e32 v213, v109, v213
	v_add_f32_e32 v212, v110, v212
	v_add_f32_e32 v213, v111, v213
	v_add_f32_e32 v212, v112, v212
	v_add_f32_e32 v213, v113, v213
	v_add_f32_e32 v212, v114, v212
	v_add_f32_e32 v213, v115, v213
	v_add_f32_e32 v212, v116, v212
	v_add_f32_e32 v213, v117, v213
	v_add_f32_e32 v212, v118, v212
	v_add_f32_e32 v213, v119, v213
	v_add_f32_e32 v212, v120, v212
	v_add_f32_e32 v213, v121, v213
	v_add_f32_e32 v212, v122, v212
	v_add_f32_e32 v213, v123, v213
	v_add_f32_e32 v212, v124, v212
	v_add_f32_e32 v213, v125, v213
	v_add_f32_e32 v212, v126, v212
	v_add_f32_e32 v213, v127, v213
	v_add_f32_e32 v212, v128, v212
	v_add_f32_e32 v213, v129, v213
	v_add_f32_e32 v212, v212, v213
	v_add_f32_e32 v255, v255, v212
	v_cvt_pk_bf16_f32 v98, v98, v99
	v_cvt_pk_bf16_f32 v99, v100, v101
	v_cvt_pk_bf16_f32 v100, v102, v103
	v_cvt_pk_bf16_f32 v101, v104, v105
	v_cvt_pk_bf16_f32 v102, v106, v107
	v_cvt_pk_bf16_f32 v103, v108, v109
	v_cvt_pk_bf16_f32 v104, v110, v111
	v_cvt_pk_bf16_f32 v105, v112, v113
	v_cvt_pk_bf16_f32 v114, v114, v115
	v_cvt_pk_bf16_f32 v115, v116, v117
	v_cvt_pk_bf16_f32 v116, v118, v119
	v_cvt_pk_bf16_f32 v117, v120, v121
	v_cvt_pk_bf16_f32 v118, v122, v123
	v_cvt_pk_bf16_f32 v119, v124, v125
	v_cvt_pk_bf16_f32 v120, v126, v127
	v_cvt_pk_bf16_f32 v121, v128, v129
	v_permlane32_swap_b32_e32 v98, v100
	v_permlane32_swap_b32_e32 v99, v101
	v_permlane32_swap_b32_e32 v102, v104
	v_permlane32_swap_b32_e32 v103, v105
	v_permlane32_swap_b32_e32 v114, v116
	v_permlane32_swap_b32_e32 v115, v117
	v_permlane32_swap_b32_e32 v118, v120
	v_permlane32_swap_b32_e32 v119, v121
	ds_read_b64_tr_b16 v[106:107], v202 offset:512
	ds_read_b64_tr_b16 v[108:109], v202 offset:2560
	ds_read_b64_tr_b16 v[110:111], v202 offset:4608
	ds_read_b64_tr_b16 v[112:113], v202 offset:6656
	ds_read_b64_tr_b16 v[122:123], v202 offset:8704
	ds_read_b64_tr_b16 v[124:125], v202 offset:10752
	ds_read_b64_tr_b16 v[126:127], v202 offset:12800
	ds_read_b64_tr_b16 v[128:129], v202 offset:14848
	s_waitcnt lgkmcnt(14)
	v_mfma_f32_32x32x16_bf16 v[0:15], v[66:69], v[74:77], v[0:15]
	v_mfma_f32_32x32x16_bf16 v[32:47], v[98:101], v[74:77], v[32:47]
	s_waitcnt lgkmcnt(12)
	v_mfma_f32_32x32x16_bf16 v[0:15], v[70:73], v[78:81], v[0:15]
	v_mfma_f32_32x32x16_bf16 v[32:47], v[102:105], v[78:81], v[32:47]
	s_waitcnt lgkmcnt(10)
	v_mfma_f32_32x32x16_bf16 v[0:15], v[82:85], v[90:93], v[0:15]
	v_mfma_f32_32x32x16_bf16 v[32:47], v[114:117], v[90:93], v[32:47]
	s_waitcnt lgkmcnt(8)
	v_mfma_f32_32x32x16_bf16 v[0:15], v[86:89], v[94:97], v[0:15]
	v_mfma_f32_32x32x16_bf16 v[32:47], v[118:121], v[94:97], v[32:47]
	s_waitcnt lgkmcnt(6)
	v_mfma_f32_32x32x16_bf16 v[16:31], v[66:69], v[106:109], v[16:31]
	v_mfma_f32_32x32x16_bf16 v[48:63], v[98:101], v[106:109], v[48:63]
	s_waitcnt lgkmcnt(4)
	v_mfma_f32_32x32x16_bf16 v[16:31], v[70:73], v[110:113], v[16:31]
	v_mfma_f32_32x32x16_bf16 v[48:63], v[102:105], v[110:113], v[48:63]
	s_waitcnt lgkmcnt(2)
	v_mfma_f32_32x32x16_bf16 v[16:31], v[82:85], v[122:125], v[16:31]
	v_mfma_f32_32x32x16_bf16 v[48:63], v[114:117], v[122:125], v[48:63]
	s_waitcnt lgkmcnt(0)
	v_mfma_f32_32x32x16_bf16 v[16:31], v[86:89], v[126:129], v[16:31]
	v_mfma_f32_32x32x16_bf16 v[48:63], v[118:121], v[126:129], v[48:63]
	s_waitcnt lgkmcnt(0)
	s_cmp_eq_u64 s[2:3], 0
	s_cbranch_scc1 .LA_g0b
	s_barrier
